# GEMM K-loop rewritten: next step fragments read during the second MFMA group, barrier between the groups
# baseline (speedup 1.0000x reference)
.LBB0_245:
	s_and_b32 s9, s76, 7
	s_add_u32 s5, s58, s50
	s_addc_u32 s6, s59, s51
	s_lshl_b32 s8, s8, 3
	s_or_b32 s8, s8, s9
	s_lshl_b32 s7, s7, 3
	s_sub_i32 s7, s8, s7
	s_lshl_b32 s8, s7, 8
	s_ashr_i32 s9, s8, 31
	s_lshl_b64 s[8:9], s[8:9], 11
	s_add_u32 s8, s56, s8
	v_mov_b32_e32 v2, 0
	s_addc_u32 s9, s57, s9
	s_mov_b32 s7, 0
	s_mov_b64 s[50:51], 0
	s_mov_b32 s100, 0
	v_mov_b32_e32 v3, v2
	v_mov_b32_e32 v4, v2
	v_mov_b32_e32 v5, v2
	v_mov_b32_e32 v6, v2
	v_mov_b32_e32 v7, v2
	v_mov_b32_e32 v8, v2
	v_mov_b32_e32 v9, v2
	v_mov_b32_e32 v10, v2
	v_mov_b32_e32 v11, v2
	v_mov_b32_e32 v12, v2
	v_mov_b32_e32 v13, v2
	v_mov_b32_e32 v14, v2
	v_mov_b32_e32 v15, v2
	v_mov_b32_e32 v16, v2
	v_mov_b32_e32 v17, v2
	v_mov_b32_e32 v22, v2
	v_mov_b32_e32 v23, v2
	v_mov_b32_e32 v24, v2
	v_mov_b32_e32 v25, v2
	v_mov_b32_e32 v30, v2
	v_mov_b32_e32 v31, v2
	v_mov_b32_e32 v32, v2
	v_mov_b32_e32 v33, v2
	v_mov_b32_e32 v38, v2
	v_mov_b32_e32 v39, v2
	v_mov_b32_e32 v40, v2
	v_mov_b32_e32 v41, v2
	v_mov_b32_e32 v46, v2
	v_mov_b32_e32 v47, v2
	v_mov_b32_e32 v48, v2
	v_mov_b32_e32 v49, v2
	v_mov_b32_e32 v18, v2
	v_mov_b32_e32 v19, v2
	v_mov_b32_e32 v20, v2
	v_mov_b32_e32 v21, v2
	v_mov_b32_e32 v26, v2
	v_mov_b32_e32 v27, v2
	v_mov_b32_e32 v28, v2
	v_mov_b32_e32 v29, v2
	v_mov_b32_e32 v34, v2
	v_mov_b32_e32 v35, v2
	v_mov_b32_e32 v36, v2
	v_mov_b32_e32 v37, v2
	v_mov_b32_e32 v42, v2
	v_mov_b32_e32 v43, v2
	v_mov_b32_e32 v44, v2
	v_mov_b32_e32 v45, v2
	v_mov_b32_e32 v54, v2
	v_mov_b32_e32 v55, v2
	v_mov_b32_e32 v56, v2
	v_mov_b32_e32 v57, v2
	v_mov_b32_e32 v62, v2
	v_mov_b32_e32 v63, v2
	v_mov_b32_e32 v64, v2
	v_mov_b32_e32 v65, v2
	v_mov_b32_e32 v70, v2
	v_mov_b32_e32 v71, v2
	v_mov_b32_e32 v72, v2
	v_mov_b32_e32 v73, v2
	v_mov_b32_e32 v78, v2
	v_mov_b32_e32 v79, v2
	v_mov_b32_e32 v80, v2
	v_mov_b32_e32 v81, v2
	v_mov_b32_e32 v50, v2
	v_mov_b32_e32 v51, v2
	v_mov_b32_e32 v52, v2
	v_mov_b32_e32 v53, v2
	v_mov_b32_e32 v58, v2
	v_mov_b32_e32 v59, v2
	v_mov_b32_e32 v60, v2
	v_mov_b32_e32 v61, v2
	v_mov_b32_e32 v66, v2
	v_mov_b32_e32 v67, v2
	v_mov_b32_e32 v68, v2
	v_mov_b32_e32 v69, v2
	v_mov_b32_e32 v74, v2
	v_mov_b32_e32 v75, v2
	v_mov_b32_e32 v76, v2
	v_mov_b32_e32 v77, v2
	v_mov_b32_e32 v86, v2
	v_mov_b32_e32 v87, v2
	v_mov_b32_e32 v88, v2
	v_mov_b32_e32 v89, v2
	v_mov_b32_e32 v94, v2
	v_mov_b32_e32 v95, v2
	v_mov_b32_e32 v96, v2
	v_mov_b32_e32 v97, v2
	v_mov_b32_e32 v102, v2
	v_mov_b32_e32 v103, v2
	v_mov_b32_e32 v104, v2
	v_mov_b32_e32 v105, v2
	v_mov_b32_e32 v110, v2
	v_mov_b32_e32 v111, v2
	v_mov_b32_e32 v112, v2
	v_mov_b32_e32 v113, v2
	v_mov_b32_e32 v82, v2
	v_mov_b32_e32 v83, v2
	v_mov_b32_e32 v84, v2
	v_mov_b32_e32 v85, v2
	v_mov_b32_e32 v90, v2
	v_mov_b32_e32 v91, v2
	v_mov_b32_e32 v92, v2
	v_mov_b32_e32 v93, v2
	v_mov_b32_e32 v98, v2
	v_mov_b32_e32 v99, v2
	v_mov_b32_e32 v100, v2
	v_mov_b32_e32 v101, v2
	v_mov_b32_e32 v106, v2
	v_mov_b32_e32 v107, v2
	v_mov_b32_e32 v108, v2
	v_mov_b32_e32 v109, v2
	v_mov_b32_e32 v114, v2
	v_mov_b32_e32 v115, v2
	v_mov_b32_e32 v116, v2
	v_mov_b32_e32 v117, v2
	v_mov_b32_e32 v118, v2
	v_mov_b32_e32 v119, v2
	v_mov_b32_e32 v120, v2
	v_mov_b32_e32 v121, v2
	v_mov_b32_e32 v122, v2
	v_mov_b32_e32 v123, v2
	v_mov_b32_e32 v124, v2
	v_mov_b32_e32 v125, v2
	v_mov_b32_e32 v126, v2
	v_mov_b32_e32 v127, v2
	v_mov_b32_e32 v128, v2
	v_mov_b32_e32 v129, v2
	v_readfirstlane_b32 s69, v147
	v_add_u32_e32 v153, s7, v150
	v_add_u32_e32 v182, s7, v149
	s_waitcnt vmcnt(6)
	s_barrier
	ds_read_b128 v[170:173], v182 offset:0
	ds_read_b128 v[174:177], v182 offset:0x400
	ds_read_b128 v[178:181], v182 offset:0x800
	ds_read_b128 v[200:203], v182 offset:0xc00
	ds_read_b128 v[154:157], v153 offset:0
	ds_read_b128 v[158:161], v153 offset:0x400
	ds_read_b128 v[162:165], v153 offset:0x800
	ds_read_b128 v[166:169], v153 offset:0xc00
	s_add_i32 s67, s69, 0xc000
	s_mov_b32 m0, s67
	s_nop 0
	global_load_lds_dwordx4 v0, s[8:9]
	s_add_u32 m0, s67, 0x400
	s_nop 0
	global_load_lds_dwordx4 v130, s[8:9]
	s_add_u32 m0, s67, 0x800
	s_nop 0
	global_load_lds_dwordx4 v132, s[8:9]
.LBB0_246:
	s_add_i32 s10, s7, 0xffffa000
	s_cmp_lg_u32 s7, 0
	s_cselect_b32 s12, s10, 0xc000
	s_add_i32 s10, s7, 0x6000
	s_cmpk_lg_u32 s7, 0xc000
	s_cselect_b32 s66, s10, 0
	s_cmpk_lg_i32 s100, 0x7400
	s_cselect_b32 s62, 1, 0
	v_add_u32_e32 v133, s7, v149
	v_add_u32_e32 v153, s66, v150
	v_add_u32_e32 v182, s66, v149
	s_add_u32 s10, s8, s50
	s_addc_u32 s11, s9, s51
	s_add_u32 s64, s5, s100
	s_addc_u32 s65, s6, 0
	s_add_u32 s70, s10, s60
	s_addc_u32 s71, s11, s61
	s_add_i32 s13, s12, s69
	s_lshr_b32 s68, s69, 1
	s_add_i32 s68, s68, s12
	s_addk_i32 s68, 0x4000
	s_add_i32 s67, s7, s69
	s_waitcnt lgkmcnt(3)
	v_mfma_f32_16x16x32_bf16 v[126:129], v[154:157], v[170:173], v[126:129]
	ds_read_b128 v[204:207], v133 offset:0x1000
	v_mfma_f32_16x16x32_bf16 v[122:125], v[154:157], v[174:177], v[122:125]
	ds_read_b128 v[208:211], v133 offset:0x1400
	v_mfma_f32_16x16x32_bf16 v[118:121], v[154:157], v[178:181], v[118:121]
	ds_read_b128 v[212:215], v133 offset:0x1800
	v_mfma_f32_16x16x32_bf16 v[114:117], v[154:157], v[200:203], v[114:117]
	ds_read_b128 v[216:219], v133 offset:0x1c00
	s_waitcnt lgkmcnt(6)
	v_mfma_f32_16x16x32_bf16 v[110:113], v[158:161], v[170:173], v[110:113]
	s_add_u32 m0, s13, 0xc00
	s_nop 0
	global_load_lds_dwordx4 v136, s[10:11]
	v_mfma_f32_16x16x32_bf16 v[102:105], v[158:161], v[174:177], v[102:105]
	v_mfma_f32_16x16x32_bf16 v[94:97], v[158:161], v[178:181], v[94:97]
	v_mfma_f32_16x16x32_bf16 v[86:89], v[158:161], v[200:203], v[86:89]
	s_waitcnt lgkmcnt(5)
	v_mfma_f32_16x16x32_bf16 v[78:81], v[162:165], v[170:173], v[78:81]
	s_mov_b32 m0, s68
	s_nop 0
	global_load_lds_dwordx4 v138, s[64:65]
	v_mfma_f32_16x16x32_bf16 v[70:73], v[162:165], v[174:177], v[70:73]
	v_mfma_f32_16x16x32_bf16 v[62:65], v[162:165], v[178:181], v[62:65]
	v_mfma_f32_16x16x32_bf16 v[54:57], v[162:165], v[200:203], v[54:57]
	s_waitcnt lgkmcnt(4)
	v_mfma_f32_16x16x32_bf16 v[46:49], v[166:169], v[170:173], v[46:49]
	s_add_u32 m0, s68, 0x400
	s_nop 0
	global_load_lds_dwordx4 v140, s[64:65]
	v_mfma_f32_16x16x32_bf16 v[38:41], v[166:169], v[174:177], v[38:41]
	v_mfma_f32_16x16x32_bf16 v[30:33], v[166:169], v[178:181], v[30:33]
	v_mfma_f32_16x16x32_bf16 v[22:25], v[166:169], v[200:203], v[22:25]
	s_waitcnt lgkmcnt(0)
	s_waitcnt vmcnt(6)
	s_barrier
	ds_read_b128 v[170:173], v182 offset:0
	ds_read_b128 v[174:177], v182 offset:0x400
	ds_read_b128 v[178:181], v182 offset:0x800
	ds_read_b128 v[200:203], v182 offset:0xc00
	v_mfma_f32_16x16x32_bf16 v[106:109], v[154:157], v[204:207], v[106:109]
	v_mfma_f32_16x16x32_bf16 v[98:101], v[154:157], v[208:211], v[98:101]
	v_mfma_f32_16x16x32_bf16 v[90:93], v[154:157], v[212:215], v[90:93]
	v_mfma_f32_16x16x32_bf16 v[82:85], v[154:157], v[216:219], v[82:85]
	ds_read_b128 v[154:157], v153 offset:0
	s_cmp_eq_u32 s62, 0
	s_cbranch_scc1 .Lkl_noearly0
	s_mov_b32 m0, s67
	s_nop 0
	global_load_lds_dwordx4 v0, s[70:71]
.Lkl_noearly0:
	v_mfma_f32_16x16x32_bf16 v[74:77], v[158:161], v[204:207], v[74:77]
	v_mfma_f32_16x16x32_bf16 v[66:69], v[158:161], v[208:211], v[66:69]
	v_mfma_f32_16x16x32_bf16 v[58:61], v[158:161], v[212:215], v[58:61]
	v_mfma_f32_16x16x32_bf16 v[50:53], v[158:161], v[216:219], v[50:53]
	ds_read_b128 v[158:161], v153 offset:0x400
	s_cmp_eq_u32 s62, 0
	s_cbranch_scc1 .Lkl_noearly1
	s_add_u32 m0, s67, 0x400
	s_nop 0
	global_load_lds_dwordx4 v130, s[70:71]
.Lkl_noearly1:
	v_mfma_f32_16x16x32_bf16 v[42:45], v[162:165], v[204:207], v[42:45]
	v_mfma_f32_16x16x32_bf16 v[34:37], v[162:165], v[208:211], v[34:37]
	v_mfma_f32_16x16x32_bf16 v[26:29], v[162:165], v[212:215], v[26:29]
	v_mfma_f32_16x16x32_bf16 v[18:21], v[162:165], v[216:219], v[18:21]
	ds_read_b128 v[162:165], v153 offset:0x800
	s_cmp_eq_u32 s62, 0
	s_cbranch_scc1 .Lkl_noearly2
	s_add_u32 m0, s67, 0x800
	s_nop 0
	global_load_lds_dwordx4 v132, s[70:71]
.Lkl_noearly2:
	v_mfma_f32_16x16x32_bf16 v[14:17], v[166:169], v[204:207], v[14:17]
	v_mfma_f32_16x16x32_bf16 v[10:13], v[166:169], v[208:211], v[10:13]
	v_mfma_f32_16x16x32_bf16 v[6:9], v[166:169], v[212:215], v[6:9]
	v_mfma_f32_16x16x32_bf16 v[2:5], v[166:169], v[216:219], v[2:5]
	ds_read_b128 v[166:169], v153 offset:0xc00
	s_mov_b32 s7, s66
	s_addk_i32 s100, 0x400
	s_add_u32 s50, s50, s60
	s_addc_u32 s51, s51, 0
	s_cmpk_lg_i32 s100, 0x7800
	s_cbranch_scc1 .LBB0_246
	s_waitcnt vmcnt(6)
	s_barrier
	v_add_u32_e32 v0, s7, v150
	v_add_u32_e32 v140, s7, v149
	ds_read_b128 v[130:133], v0 offset:0
	ds_read_b128 v[136:139], v0 offset:0x400
	ds_read_b128 v[154:157], v0 offset:0x800
	ds_read_b128 v[158:161], v0 offset:0xc00
	ds_read_b128 v[162:165], v140 offset:0
	ds_read_b128 v[166:169], v140 offset:0x400
	ds_read_b128 v[170:173], v140 offset:0x800
	ds_read_b128 v[174:177], v140 offset:0xc00
	ds_read_b128 v[178:181], v140 offset:0x1000
	ds_read_b128 v[200:203], v140 offset:0x1400
	ds_read_b128 v[204:207], v140 offset:0x1800
	ds_read_b128 v[208:211], v140 offset:0x1c00
	s_lshl_b32 s49, s4, 8
	s_waitcnt lgkmcnt(4)
	s_nop 0
	v_mfma_f32_16x16x32_bf16 v[126:129], v[130:133], v[162:165], v[126:129]
	v_mfma_f32_16x16x32_bf16 v[118:121], v[130:133], v[170:173], v[118:121]
	v_mfma_f32_16x16x32_bf16 v[114:117], v[130:133], v[174:177], v[114:117]
	v_mfma_f32_16x16x32_bf16 v[110:113], v[136:139], v[162:165], v[110:113]
	v_mfma_f32_16x16x32_bf16 v[102:105], v[136:139], v[166:169], v[102:105]
	v_mfma_f32_16x16x32_bf16 v[94:97], v[136:139], v[170:173], v[94:97]
	v_mfma_f32_16x16x32_bf16 v[86:89], v[136:139], v[174:177], v[86:89]
	v_mfma_f32_16x16x32_bf16 v[70:73], v[154:157], v[166:169], v[70:73]
	v_mfma_f32_16x16x32_bf16 v[62:65], v[154:157], v[170:173], v[62:65]
	v_mfma_f32_16x16x32_bf16 v[54:57], v[154:157], v[174:177], v[54:57]
	v_mfma_f32_16x16x32_bf16 v[46:49], v[158:161], v[162:165], v[46:49]
	v_mfma_f32_16x16x32_bf16 v[38:41], v[158:161], v[166:169], v[38:41]
	v_mfma_f32_16x16x32_bf16 v[30:33], v[158:161], v[170:173], v[30:33]
	v_mfma_f32_16x16x32_bf16 v[22:25], v[158:161], v[174:177], v[22:25]
	v_mfma_f32_16x16x32_bf16 v[212:215], v[130:133], v[166:169], v[122:125]
	v_mfma_f32_16x16x32_bf16 v[216:219], v[154:157], v[162:165], v[78:81]
	s_waitcnt lgkmcnt(0)
	s_nop 0
	v_mfma_f32_16x16x32_bf16 v[174:177], v[136:139], v[178:181], v[74:77]
	v_mfma_f32_16x16x32_bf16 v[220:223], v[136:139], v[200:203], v[66:69]
	v_mfma_f32_16x16x32_bf16 v[224:227], v[136:139], v[204:207], v[58:61]
	v_mfma_f32_16x16x32_bf16 v[50:53], v[136:139], v[208:211], v[50:53]
	v_mfma_f32_16x16x32_bf16 v[136:139], v[154:157], v[178:181], v[42:45]
	v_mfma_f32_16x16x32_bf16 v[34:37], v[154:157], v[200:203], v[34:37]
	v_mfma_f32_16x16x32_bf16 v[6:9], v[158:161], v[204:207], v[6:9]
	v_mfma_f32_16x16x32_bf16 v[162:165], v[130:133], v[178:181], v[106:109]
	v_mfma_f32_16x16x32_bf16 v[166:169], v[130:133], v[200:203], v[98:101]
	v_mfma_f32_16x16x32_bf16 v[170:173], v[130:133], v[204:207], v[90:93]
	v_mfma_f32_16x16x32_bf16 v[130:133], v[130:133], v[208:211], v[82:85]
	v_mfma_f32_16x16x32_bf16 v[228:231], v[154:157], v[204:207], v[26:29]
	v_mfma_f32_16x16x32_bf16 v[154:157], v[154:157], v[208:211], v[18:21]
	v_mfma_f32_16x16x32_bf16 v[178:181], v[158:161], v[178:181], v[14:17]
	v_mfma_f32_16x16x32_bf16 v[200:203], v[158:161], v[200:203], v[10:13]
	v_mfma_f32_16x16x32_bf16 v[158:161], v[158:161], v[208:211], v[2:5]
	s_waitcnt vmcnt(0)
	s_barrier
	ds_read_b128 v[2:5], v151 offset:0
	ds_read_b128 v[14:17], v151 offset:0x400
	ds_read_b128 v[204:207], v151 offset:0x800
	ds_read_b128 v[208:211], v151 offset:0xc00
	ds_read_b128 v[10:13], v152 offset:0
	ds_read_b128 v[18:21], v152 offset:0x400
	ds_read_b128 v[26:29], v152 offset:0x800
	ds_read_b128 v[42:45], v152 offset:0xc00
	ds_read_b128 v[232:235], v152 offset:0x1000
	ds_read_b128 v[236:239], v152 offset:0x1400
	ds_read_b128 v[240:243], v152 offset:0x1800
	ds_read_b128 v[244:247], v152 offset:0x1c00
	s_nop 0
	s_waitcnt lgkmcnt(4)
	s_nop 0
	v_mfma_f32_16x16x32_bf16 v[122:125], v[2:5], v[10:13], v[126:129]
	v_mfma_f32_16x16x32_bf16 v[106:109], v[2:5], v[18:21], v[212:215]
	v_mfma_f32_16x16x32_bf16 v[90:93], v[2:5], v[26:29], v[118:121]
	v_mfma_f32_16x16x32_bf16 v[74:77], v[2:5], v[42:45], v[114:117]
	v_mfma_f32_16x16x32_bf16 v[126:129], v[14:17], v[10:13], v[110:113]
	v_mfma_f32_16x16x32_bf16 v[110:113], v[14:17], v[18:21], v[102:105]
	v_mfma_f32_16x16x32_bf16 v[94:97], v[14:17], v[26:29], v[94:97]
	v_mfma_f32_16x16x32_bf16 v[78:81], v[14:17], v[42:45], v[86:89]
	v_mfma_f32_16x16x32_bf16 v[114:117], v[204:207], v[10:13], v[216:219]
	v_mfma_f32_16x16x32_bf16 v[98:101], v[204:207], v[18:21], v[70:73]
	v_mfma_f32_16x16x32_bf16 v[82:85], v[204:207], v[26:29], v[62:65]
	v_mfma_f32_16x16x32_bf16 v[66:69], v[204:207], v[42:45], v[54:57]
	v_mfma_f32_16x16x32_bf16 v[118:121], v[208:211], v[10:13], v[46:49]
	v_mfma_f32_16x16x32_bf16 v[102:105], v[208:211], v[18:21], v[38:41]
	v_mfma_f32_16x16x32_bf16 v[86:89], v[208:211], v[26:29], v[30:33]
	v_mfma_f32_16x16x32_bf16 v[70:73], v[208:211], v[42:45], v[22:25]
	s_waitcnt lgkmcnt(0)
	s_nop 0
	v_mfma_f32_16x16x32_bf16 v[58:61], v[2:5], v[232:235], v[162:165]
	v_mfma_f32_16x16x32_bf16 v[42:45], v[2:5], v[236:239], v[166:169]
	v_mfma_f32_16x16x32_bf16 v[26:29], v[2:5], v[240:243], v[170:173]
	v_mfma_f32_16x16x32_bf16 v[10:13], v[2:5], v[244:247], v[130:133]
	v_mfma_f32_16x16x32_bf16 v[62:65], v[14:17], v[232:235], v[174:177]
	v_mfma_f32_16x16x32_bf16 v[46:49], v[14:17], v[236:239], v[220:223]
	v_mfma_f32_16x16x32_bf16 v[30:33], v[14:17], v[240:243], v[224:227]
	v_mfma_f32_16x16x32_bf16 v[14:17], v[14:17], v[244:247], v[50:53]
	v_mfma_f32_16x16x32_bf16 v[50:53], v[204:207], v[232:235], v[136:139]
	v_mfma_f32_16x16x32_bf16 v[34:37], v[204:207], v[236:239], v[34:37]
	v_mfma_f32_16x16x32_bf16 v[18:21], v[204:207], v[240:243], v[228:231]
	v_mfma_f32_16x16x32_bf16 v[2:5], v[204:207], v[244:247], v[154:157]
	v_mfma_f32_16x16x32_bf16 v[54:57], v[208:211], v[232:235], v[178:181]
	v_mfma_f32_16x16x32_bf16 v[38:41], v[208:211], v[236:239], v[200:203]
	v_mfma_f32_16x16x32_bf16 v[22:25], v[208:211], v[240:243], v[6:9]
	v_mfma_f32_16x16x32_bf16 v[6:9], v[208:211], v[244:247], v[158:161]
	v_mov_b32_e32 v136, v134
	s_mov_b64 s[50:51], -1
	s_and_b64 vcc, exec, s[22:23]
	s_barrier
	s_cbranch_vccz .LBB0_264
	s_and_b64 vcc, exec, s[0:1]
	s_cbranch_vccz .LBB0_250
	v_lshrrev_b32_e32 v0, 6, v136
	v_mul_lo_u32 v137, v0, s14
	v_and_b32_e32 v130, 15, v136
	v_and_or_b32 v0, v136, 48, v137
	s_movk_i32 s4, 0x90
	v_mad_u32_u24 v0, v130, s4, v0
	v_cvt_pk_bf16_f32 v130, v122, v123
	v_cvt_pk_bf16_f32 v131, v124, v125
	v_cvt_pk_bf16_f32 v132, v126, v127
	v_cvt_pk_bf16_f32 v133, v128, v129
	s_waitcnt vmcnt(0)
	ds_write_b128 v0, v[130:133]
	v_cvt_pk_bf16_f32 v130, v114, v115
	v_cvt_pk_bf16_f32 v131, v116, v117
	v_cvt_pk_bf16_f32 v132, v118, v119
	v_cvt_pk_bf16_f32 v133, v120, v121
	ds_write_b128 v0, v[130:133] offset:64
	v_cvt_pk_bf16_f32 v130, v106, v107
	v_cvt_pk_bf16_f32 v131, v108, v109
	v_cvt_pk_bf16_f32 v132, v110, v111
	v_cvt_pk_bf16_f32 v133, v112, v113
	ds_write_b128 v0, v[130:133] offset:2304
	v_cvt_pk_bf16_f32 v130, v98, v99
	v_cvt_pk_bf16_f32 v131, v100, v101
	v_cvt_pk_bf16_f32 v132, v102, v103
	v_cvt_pk_bf16_f32 v133, v104, v105
	ds_write_b128 v0, v[130:133] offset:2368
	v_cvt_pk_bf16_f32 v130, v90, v91
	v_cvt_pk_bf16_f32 v131, v92, v93
	v_cvt_pk_bf16_f32 v132, v94, v95
	v_cvt_pk_bf16_f32 v133, v96, v97
	ds_write_b128 v0, v[130:133] offset:4608
	v_cvt_pk_bf16_f32 v130, v82, v83
	v_cvt_pk_bf16_f32 v131, v84, v85
	v_cvt_pk_bf16_f32 v132, v86, v87
	v_cvt_pk_bf16_f32 v133, v88, v89
	ds_write_b128 v0, v[130:133] offset:4672
	v_cvt_pk_bf16_f32 v130, v74, v75
	v_cvt_pk_bf16_f32 v131, v76, v77
	v_cvt_pk_bf16_f32 v132, v78, v79
	v_cvt_pk_bf16_f32 v133, v80, v81
	ds_write_b128 v0, v[130:133] offset:6912
	v_cvt_pk_bf16_f32 v130, v66, v67
	v_cvt_pk_bf16_f32 v131, v68, v69
	v_cvt_pk_bf16_f32 v132, v70, v71
	v_cvt_pk_bf16_f32 v133, v72, v73
	ds_write_b128 v0, v[130:133] offset:6976
	v_cvt_pk_bf16_f32 v130, v58, v59
	v_cvt_pk_bf16_f32 v131, v60, v61
	v_cvt_pk_bf16_f32 v132, v62, v63
	v_cvt_pk_bf16_f32 v133, v64, v65
	ds_write_b128 v0, v[130:133] offset:9216
	v_cvt_pk_bf16_f32 v130, v50, v51
	v_cvt_pk_bf16_f32 v131, v52, v53
	v_cvt_pk_bf16_f32 v132, v54, v55
	v_cvt_pk_bf16_f32 v133, v56, v57
	ds_write_b128 v0, v[130:133] offset:9280
	v_cvt_pk_bf16_f32 v130, v42, v43
	v_cvt_pk_bf16_f32 v131, v44, v45
	v_cvt_pk_bf16_f32 v132, v46, v47
	v_cvt_pk_bf16_f32 v133, v48, v49
	ds_write_b128 v0, v[130:133] offset:11520
	v_cvt_pk_bf16_f32 v130, v34, v35
	v_cvt_pk_bf16_f32 v131, v36, v37
	v_cvt_pk_bf16_f32 v132, v38, v39
	v_cvt_pk_bf16_f32 v133, v40, v41
	ds_write_b128 v0, v[130:133] offset:11584
	v_cvt_pk_bf16_f32 v130, v26, v27
	v_cvt_pk_bf16_f32 v131, v28, v29
	v_cvt_pk_bf16_f32 v132, v30, v31
	v_cvt_pk_bf16_f32 v133, v32, v33
	ds_write_b128 v0, v[130:133] offset:13824
	v_cvt_pk_bf16_f32 v130, v18, v19
	v_cvt_pk_bf16_f32 v131, v20, v21
	v_cvt_pk_bf16_f32 v132, v22, v23
	v_cvt_pk_bf16_f32 v133, v24, v25
	ds_write_b128 v0, v[130:133] offset:13888
	v_cvt_pk_bf16_f32 v130, v10, v11
	v_cvt_pk_bf16_f32 v131, v12, v13
	v_cvt_pk_bf16_f32 v132, v14, v15
	v_cvt_pk_bf16_f32 v133, v16, v17
	ds_write_b128 v0, v[130:133] offset:16128
	v_cvt_pk_bf16_f32 v130, v2, v3
	v_cvt_pk_bf16_f32 v131, v4, v5
	v_cvt_pk_bf16_f32 v132, v6, v7
	v_cvt_pk_bf16_f32 v133, v8, v9
	ds_write_b128 v0, v[130:133] offset:16192
	v_and_b32_e32 v0, 0xffffff80, v136
	v_add_u32_e32 v130, s48, v0
	v_ashrrev_i32_e32 v131, 31, v130
	v_lshlrev_b64 v[130:131], 11, v[130:131]
	v_lshl_add_u64 v[130:131], s[38:39], 0, v[130:131]
	v_and_b32_e32 v0, 64, v136
	v_lshl_add_u64 v[130:131], s[46:47], 1, v[130:131]
	v_lshlrev_b32_e32 v0, 1, v0
	v_lshl_add_u64 v[138:139], v[130:131], 0, v[0:1]
	v_lshlrev_b32_e32 v0, 4, v136
	v_and_b32_e32 v0, 0x70, v0
	v_bfe_u32 v140, v136, 3, 3
	v_or_b32_e32 v130, v137, v0
	s_waitcnt lgkmcnt(0)
	v_mad_u32_u24 v137, v140, s4, v130
	ds_read_b128 v[130:133], v137
	v_lshl_add_u64 v[138:139], v[138:139], 0, v[0:1]
	v_lshlrev_b32_e32 v0, 11, v140
	v_lshl_add_u64 v[140:141], v[138:139], 0, v[0:1]
	s_mov_b64 s[50:51], 0
	s_waitcnt lgkmcnt(0)
	global_store_dwordx4 v[140:141], v[130:133], off
	ds_read_b128 v[130:133], v137 offset:1152
	v_or_b32_e32 v140, 0x4000, v0
	v_mov_b32_e32 v141, v1
	v_lshl_add_u64 v[140:141], v[138:139], 0, v[140:141]
	s_waitcnt lgkmcnt(0)
	global_store_dwordx4 v[140:141], v[130:133], off
	ds_read_b128 v[130:133], v137 offset:2304
	v_or_b32_e32 v140, 0x8000, v0
	v_mov_b32_e32 v141, v1
	v_lshl_add_u64 v[140:141], v[138:139], 0, v[140:141]
	s_waitcnt lgkmcnt(0)
	global_store_dwordx4 v[140:141], v[130:133], off
	ds_read_b128 v[130:133], v137 offset:3456
	v_or_b32_e32 v140, 0xc000, v0
	v_mov_b32_e32 v141, v1
	v_lshl_add_u64 v[140:141], v[138:139], 0, v[140:141]
	s_waitcnt lgkmcnt(0)
	global_store_dwordx4 v[140:141], v[130:133], off
	ds_read_b128 v[130:133], v137 offset:4608
	v_or_b32_e32 v140, 0x10000, v0
	v_mov_b32_e32 v141, v1
	v_lshl_add_u64 v[140:141], v[138:139], 0, v[140:141]
	s_waitcnt lgkmcnt(0)
	global_store_dwordx4 v[140:141], v[130:133], off
	ds_read_b128 v[130:133], v137 offset:5760
	v_or_b32_e32 v140, 0x14000, v0
	v_mov_b32_e32 v141, v1
	v_lshl_add_u64 v[140:141], v[138:139], 0, v[140:141]
	s_waitcnt lgkmcnt(0)
	global_store_dwordx4 v[140:141], v[130:133], off
	ds_read_b128 v[130:133], v137 offset:6912
	v_or_b32_e32 v140, 0x18000, v0
	v_mov_b32_e32 v141, v1
	v_lshl_add_u64 v[140:141], v[138:139], 0, v[140:141]
	s_waitcnt lgkmcnt(0)
	global_store_dwordx4 v[140:141], v[130:133], off
	ds_read_b128 v[130:133], v137 offset:8064
	v_or_b32_e32 v140, 0x1c000, v0
	v_mov_b32_e32 v141, v1
	v_lshl_add_u64 v[140:141], v[138:139], 0, v[140:141]
	s_waitcnt lgkmcnt(0)
	global_store_dwordx4 v[140:141], v[130:133], off
	ds_read_b128 v[130:133], v137 offset:9216
	v_or_b32_e32 v140, 0x20000, v0
	v_mov_b32_e32 v141, v1
	v_lshl_add_u64 v[140:141], v[138:139], 0, v[140:141]
	s_waitcnt lgkmcnt(0)
	global_store_dwordx4 v[140:141], v[130:133], off
	ds_read_b128 v[130:133], v137 offset:10368
	v_or_b32_e32 v140, 0x24000, v0
	v_mov_b32_e32 v141, v1
	v_lshl_add_u64 v[140:141], v[138:139], 0, v[140:141]
	s_waitcnt lgkmcnt(0)
	global_store_dwordx4 v[140:141], v[130:133], off
	ds_read_b128 v[130:133], v137 offset:11520
	v_or_b32_e32 v140, 0x28000, v0
	v_mov_b32_e32 v141, v1
	v_lshl_add_u64 v[140:141], v[138:139], 0, v[140:141]
	s_waitcnt lgkmcnt(0)
	global_store_dwordx4 v[140:141], v[130:133], off
	ds_read_b128 v[130:133], v137 offset:12672
	v_or_b32_e32 v140, 0x2c000, v0
	v_mov_b32_e32 v141, v1
	v_lshl_add_u64 v[140:141], v[138:139], 0, v[140:141]
	s_waitcnt lgkmcnt(0)
	global_store_dwordx4 v[140:141], v[130:133], off
	ds_read_b128 v[130:133], v137 offset:13824
	v_or_b32_e32 v140, 0x30000, v0
	v_mov_b32_e32 v141, v1
	v_lshl_add_u64 v[140:141], v[138:139], 0, v[140:141]
	s_waitcnt lgkmcnt(0)
	global_store_dwordx4 v[140:141], v[130:133], off
	ds_read_b128 v[130:133], v137 offset:14976
	v_or_b32_e32 v140, 0x34000, v0
	v_mov_b32_e32 v141, v1
	v_lshl_add_u64 v[140:141], v[138:139], 0, v[140:141]
	s_waitcnt lgkmcnt(0)
	global_store_dwordx4 v[140:141], v[130:133], off
	ds_read_b128 v[130:133], v137 offset:16128
	v_or_b32_e32 v140, 0x38000, v0
	v_mov_b32_e32 v141, v1
	v_lshl_add_u64 v[140:141], v[138:139], 0, v[140:141]
	v_or_b32_e32 v0, 0x3c000, v0
	s_waitcnt lgkmcnt(0)
	global_store_dwordx4 v[140:141], v[130:133], off
	ds_read_b128 v[130:133], v137 offset:17280
	v_lshl_add_u64 v[138:139], v[138:139], 0, v[0:1]
	s_waitcnt lgkmcnt(0)
	global_store_dwordx4 v[138:139], v[130:133], off
	s_waitcnt lgkmcnt(0)
	s_barrier
